# HGRN pass3: batched double-buffered span fold + input prefetch no longer waited at the load site
# speedup vs baseline: 1.0163x; 1.0163x over previous
.LBB0_346:
	v_lshl_add_u64 v[42:43], s[62:63], 0, v[0:1]
	s_mov_b32 s6, 0x1ec00000
	v_add_co_u32_e32 v50, vcc, s6, v42
	v_lshl_add_u64 v[46:47], s[62:63], 0, v[4:5]
	s_nop 0
	v_addc_co_u32_e32 v51, vcc, 0, v43, vcc
	s_mov_b32 s6, 0x1dc00000
	v_add_co_u32_e32 v52, vcc, s6, v46
	s_nop 1
	v_addc_co_u32_e32 v53, vcc, 0, v47, vcc
	s_mov_b32 s6, 0x1dc01000
	v_add_co_u32_e32 v54, vcc, s6, v46
	s_nop 1
	v_addc_co_u32_e32 v55, vcc, 0, v47, vcc
	s_mov_b64 s[6:7], 0x200
	v_lshl_add_u64 v[0:1], v[0:1], 0, s[6:7]
	v_lshl_add_u64 v[4:5], v[4:5], 0, s[86:87]
	global_load_dwordx4 v[84:87], v[50:51], off
	global_load_dwordx4 v[88:91], v[52:53], off
	global_load_dwordx4 v[92:95], v[50:51], off offset:64
	global_load_dwordx4 v[96:99], v[52:53], off offset:1024
	global_load_dwordx4 v[100:103], v[50:51], off offset:128
	global_load_dwordx4 v[104:107], v[52:53], off offset:2048
	global_load_dwordx4 v[108:111], v[50:51], off offset:192
	global_load_dwordx4 v[112:115], v[52:53], off offset:3072
	global_load_dwordx4 v[116:119], v[50:51], off offset:256
	global_load_dwordx4 v[120:123], v[54:55], off
	global_load_dwordx4 v[124:127], v[50:51], off offset:320
	global_load_dwordx4 v[128:131], v[54:55], off offset:1024
	global_load_dwordx4 v[132:135], v[50:51], off offset:384
	global_load_dwordx4 v[136:139], v[54:55], off offset:2048
	global_load_dwordx4 v[140:143], v[50:51], off offset:448
	global_load_dwordx4 v[144:147], v[54:55], off offset:3072
.Lfold_top:
	s_add_i32 s1, s1, -1
	s_cmp_eq_u32 s1, 0
	s_cbranch_scc1 .Lfold_lastA
	v_lshl_add_u64 v[42:43], s[62:63], 0, v[0:1]
	s_mov_b32 s6, 0x1ec00000
	v_add_co_u32_e32 v50, vcc, s6, v42
	v_lshl_add_u64 v[46:47], s[62:63], 0, v[4:5]
	s_nop 0
	v_addc_co_u32_e32 v51, vcc, 0, v43, vcc
	s_mov_b32 s6, 0x1dc00000
	v_add_co_u32_e32 v52, vcc, s6, v46
	s_nop 1
	v_addc_co_u32_e32 v53, vcc, 0, v47, vcc
	s_mov_b32 s6, 0x1dc01000
	v_add_co_u32_e32 v54, vcc, s6, v46
	s_nop 1
	v_addc_co_u32_e32 v55, vcc, 0, v47, vcc
	s_mov_b64 s[6:7], 0x200
	v_lshl_add_u64 v[0:1], v[0:1], 0, s[6:7]
	v_lshl_add_u64 v[4:5], v[4:5], 0, s[86:87]
	global_load_dwordx4 v[190:193], v[50:51], off
	global_load_dwordx4 v[194:197], v[52:53], off
	global_load_dwordx4 v[198:201], v[50:51], off offset:64
	global_load_dwordx4 v[202:205], v[52:53], off offset:1024
	global_load_dwordx4 v[206:209], v[50:51], off offset:128
	global_load_dwordx4 v[210:213], v[52:53], off offset:2048
	global_load_dwordx4 v[214:217], v[50:51], off offset:192
	global_load_dwordx4 v[218:221], v[52:53], off offset:3072
	global_load_dwordx4 v[222:225], v[50:51], off offset:256
	global_load_dwordx4 v[226:229], v[54:55], off
	global_load_dwordx4 v[230:233], v[50:51], off offset:320
	global_load_dwordx4 v[234:237], v[54:55], off offset:1024
	global_load_dwordx4 v[238:241], v[50:51], off offset:384
	global_load_dwordx4 v[242:245], v[54:55], off offset:2048
	global_load_dwordx4 v[246:249], v[50:51], off offset:448
	global_load_dwordx4 v[56:59], v[54:55], off offset:3072
	s_waitcnt vmcnt(16)
	v_pk_fma_f32 v[38:39], v[38:39], v[86:87], v[90:91]
	v_pk_fma_f32 v[36:37], v[36:37], v[84:85], v[88:89]
	v_pk_fma_f32 v[34:35], v[34:35], v[94:95], v[98:99]
	v_pk_fma_f32 v[32:33], v[32:33], v[92:93], v[96:97]
	v_pk_fma_f32 v[30:31], v[30:31], v[102:103], v[106:107]
	v_pk_fma_f32 v[28:29], v[28:29], v[100:101], v[104:105]
	v_pk_fma_f32 v[26:27], v[26:27], v[110:111], v[114:115]
	v_pk_fma_f32 v[24:25], v[24:25], v[108:109], v[112:113]
	v_pk_fma_f32 v[22:23], v[22:23], v[118:119], v[122:123]
	v_pk_fma_f32 v[20:21], v[20:21], v[116:117], v[120:121]
	v_pk_fma_f32 v[18:19], v[18:19], v[126:127], v[130:131]
	v_pk_fma_f32 v[16:17], v[16:17], v[124:125], v[128:129]
	v_pk_fma_f32 v[14:15], v[14:15], v[134:135], v[138:139]
	v_pk_fma_f32 v[12:13], v[12:13], v[132:133], v[136:137]
	v_pk_fma_f32 v[10:11], v[10:11], v[142:143], v[146:147]
	v_pk_fma_f32 v[8:9], v[8:9], v[140:141], v[144:145]
	s_add_i32 s1, s1, -1
	s_cmp_eq_u32 s1, 0
	s_cbranch_scc1 .Lfold_lastB
	v_lshl_add_u64 v[42:43], s[62:63], 0, v[0:1]
	s_mov_b32 s6, 0x1ec00000
	v_add_co_u32_e32 v50, vcc, s6, v42
	v_lshl_add_u64 v[46:47], s[62:63], 0, v[4:5]
	s_nop 0
	v_addc_co_u32_e32 v51, vcc, 0, v43, vcc
	s_mov_b32 s6, 0x1dc00000
	v_add_co_u32_e32 v52, vcc, s6, v46
	s_nop 1
	v_addc_co_u32_e32 v53, vcc, 0, v47, vcc
	s_mov_b32 s6, 0x1dc01000
	v_add_co_u32_e32 v54, vcc, s6, v46
	s_nop 1
	v_addc_co_u32_e32 v55, vcc, 0, v47, vcc
	s_mov_b64 s[6:7], 0x200
	v_lshl_add_u64 v[0:1], v[0:1], 0, s[6:7]
	v_lshl_add_u64 v[4:5], v[4:5], 0, s[86:87]
	global_load_dwordx4 v[84:87], v[50:51], off
	global_load_dwordx4 v[88:91], v[52:53], off
	global_load_dwordx4 v[92:95], v[50:51], off offset:64
	global_load_dwordx4 v[96:99], v[52:53], off offset:1024
	global_load_dwordx4 v[100:103], v[50:51], off offset:128
	global_load_dwordx4 v[104:107], v[52:53], off offset:2048
	global_load_dwordx4 v[108:111], v[50:51], off offset:192
	global_load_dwordx4 v[112:115], v[52:53], off offset:3072
	global_load_dwordx4 v[116:119], v[50:51], off offset:256
	global_load_dwordx4 v[120:123], v[54:55], off
	global_load_dwordx4 v[124:127], v[50:51], off offset:320
	global_load_dwordx4 v[128:131], v[54:55], off offset:1024
	global_load_dwordx4 v[132:135], v[50:51], off offset:384
	global_load_dwordx4 v[136:139], v[54:55], off offset:2048
	global_load_dwordx4 v[140:143], v[50:51], off offset:448
	global_load_dwordx4 v[144:147], v[54:55], off offset:3072
	s_waitcnt vmcnt(16)
	v_pk_fma_f32 v[38:39], v[38:39], v[192:193], v[196:197]
	v_pk_fma_f32 v[36:37], v[36:37], v[190:191], v[194:195]
	v_pk_fma_f32 v[34:35], v[34:35], v[200:201], v[204:205]
	v_pk_fma_f32 v[32:33], v[32:33], v[198:199], v[202:203]
	v_pk_fma_f32 v[30:31], v[30:31], v[208:209], v[212:213]
	v_pk_fma_f32 v[28:29], v[28:29], v[206:207], v[210:211]
	v_pk_fma_f32 v[26:27], v[26:27], v[216:217], v[220:221]
	v_pk_fma_f32 v[24:25], v[24:25], v[214:215], v[218:219]
	v_pk_fma_f32 v[22:23], v[22:23], v[224:225], v[228:229]
	v_pk_fma_f32 v[20:21], v[20:21], v[222:223], v[226:227]
	v_pk_fma_f32 v[18:19], v[18:19], v[232:233], v[236:237]
	v_pk_fma_f32 v[16:17], v[16:17], v[230:231], v[234:235]
	v_pk_fma_f32 v[14:15], v[14:15], v[240:241], v[244:245]
	v_pk_fma_f32 v[12:13], v[12:13], v[238:239], v[242:243]
	v_pk_fma_f32 v[10:11], v[10:11], v[248:249], v[58:59]
	v_pk_fma_f32 v[8:9], v[8:9], v[246:247], v[56:57]
	s_branch .Lfold_top
.Lfold_lastA:
	s_waitcnt vmcnt(0)
	v_pk_fma_f32 v[38:39], v[38:39], v[86:87], v[90:91]
	v_pk_fma_f32 v[36:37], v[36:37], v[84:85], v[88:89]
	v_pk_fma_f32 v[34:35], v[34:35], v[94:95], v[98:99]
	v_pk_fma_f32 v[32:33], v[32:33], v[92:93], v[96:97]
	v_pk_fma_f32 v[30:31], v[30:31], v[102:103], v[106:107]
	v_pk_fma_f32 v[28:29], v[28:29], v[100:101], v[104:105]
	v_pk_fma_f32 v[26:27], v[26:27], v[110:111], v[114:115]
	v_pk_fma_f32 v[24:25], v[24:25], v[108:109], v[112:113]
	v_pk_fma_f32 v[22:23], v[22:23], v[118:119], v[122:123]
	v_pk_fma_f32 v[20:21], v[20:21], v[116:117], v[120:121]
	v_pk_fma_f32 v[18:19], v[18:19], v[126:127], v[130:131]
	v_pk_fma_f32 v[16:17], v[16:17], v[124:125], v[128:129]
	v_pk_fma_f32 v[14:15], v[14:15], v[134:135], v[138:139]
	v_pk_fma_f32 v[12:13], v[12:13], v[132:133], v[136:137]
	v_pk_fma_f32 v[10:11], v[10:11], v[142:143], v[146:147]
	v_pk_fma_f32 v[8:9], v[8:9], v[140:141], v[144:145]
	s_branch .LBB0_349
.Lfold_lastB:
	s_waitcnt vmcnt(0)
	v_pk_fma_f32 v[38:39], v[38:39], v[192:193], v[196:197]
	v_pk_fma_f32 v[36:37], v[36:37], v[190:191], v[194:195]
	v_pk_fma_f32 v[34:35], v[34:35], v[200:201], v[204:205]
	v_pk_fma_f32 v[32:33], v[32:33], v[198:199], v[202:203]
	v_pk_fma_f32 v[30:31], v[30:31], v[208:209], v[212:213]
	v_pk_fma_f32 v[28:29], v[28:29], v[206:207], v[210:211]
	v_pk_fma_f32 v[26:27], v[26:27], v[216:217], v[220:221]
	v_pk_fma_f32 v[24:25], v[24:25], v[214:215], v[218:219]
	v_pk_fma_f32 v[22:23], v[22:23], v[224:225], v[228:229]
	v_pk_fma_f32 v[20:21], v[20:21], v[222:223], v[226:227]
	v_pk_fma_f32 v[18:19], v[18:19], v[232:233], v[236:237]
	v_pk_fma_f32 v[16:17], v[16:17], v[230:231], v[234:235]
	v_pk_fma_f32 v[14:15], v[14:15], v[240:241], v[244:245]
	v_pk_fma_f32 v[12:13], v[12:13], v[238:239], v[242:243]
	v_pk_fma_f32 v[10:11], v[10:11], v[248:249], v[58:59]
	v_pk_fma_f32 v[8:9], v[8:9], v[246:247], v[56:57]
	s_branch .LBB0_349

.LBB0_349:
	s_ashr_i32 s52, s18, 5
	s_lshl_b32 s6, s19, 8
	s_lshl_b32 s10, s52, 11
	v_ashrrev_i32_e32 v83, 7, v3
	s_and_b32 s7, s8, 3
	s_or_b32 s6, s6, s10
	v_lshlrev_b32_e32 v78, 2, v83
	s_lshl_b32 s1, s9, 8
	v_and_b32_e32 v0, 0x7f, v3
	v_add_u32_e32 v1, s6, v78
	s_lshl_b32 s6, s7, 8
	v_lshl_or_b32 v4, s7, 7, v0
	s_add_u32 s8, s80, s6
	v_lshlrev_b32_e32 v50, 1, v4
	v_lshlrev_b32_e32 v52, 2, v4
	s_addc_u32 s9, s81, 0
	v_lshlrev_b32_e32 v4, 1, v0
	v_mov_b32_e32 v5, v2
	v_lshl_add_u64 v[54:55], s[8:9], 0, v[4:5]
	v_mov_b64_e32 v[4:5], s[82:83]
	v_or_b32_e32 v56, 1, v1
	v_or_b32_e32 v66, 2, v1
	v_mov_b32_e32 v51, v2
	v_mov_b32_e32 v53, v2
	v_mad_i64_i32 v[6:7], s[12:13], v1, s96, v[4:5]
	v_mad_i64_i32 v[46:47], s[12:13], v56, s96, v[4:5]
	v_mad_i64_i32 v[58:59], s[12:13], v56, s30, v[54:55]
	v_mad_i64_i32 v[56:57], s[12:13], v66, s96, v[4:5]
	v_lshl_add_u64 v[42:43], v[6:7], 0, v[50:51]
	v_lshl_add_u64 v[6:7], v[6:7], 0, v[52:53]
	v_lshl_add_u64 v[48:49], v[46:47], 0, v[50:51]
	v_lshl_add_u64 v[60:61], v[56:57], 0, v[52:53]
	v_mad_i64_i32 v[44:45], s[12:13], v1, s30, v[54:55]
	v_lshl_add_u64 v[46:47], v[46:47], 0, v[52:53]
	v_lshl_add_u64 v[62:63], v[56:57], 0, v[50:51]
	global_load_dword v56, v[6:7], off
	global_load_ushort v84, v[44:45], off
	global_load_ushort v67, v[48:49], off offset:2048
	global_load_dword v57, v[46:47], off
	s_waitcnt lgkmcnt(0)
	global_load_ushort v85, v[58:59], off
	s_nop 0
	global_load_dword v60, v[60:61], off
	s_nop 0
	global_load_ushort v68, v[62:63], off offset:2048
	global_load_ushort v69, v[42:43], off offset:2048
	v_or_b32_e32 v70, 3, v1
	v_add_u32_e32 v48, 16, v1
	v_mad_i64_i32 v[6:7], s[12:13], v70, s96, v[4:5]
	v_mad_i64_i32 v[44:45], s[12:13], v48, s96, v[4:5]
	v_add_u32_e32 v71, 17, v1
	v_lshl_add_u64 v[42:43], v[6:7], 0, v[50:51]
	v_lshl_add_u64 v[46:47], v[44:45], 0, v[50:51]
	v_mad_i64_i32 v[62:63], s[12:13], v71, s96, v[4:5]
	v_lshl_add_u64 v[6:7], v[6:7], 0, v[52:53]
	v_lshl_add_u64 v[44:45], v[44:45], 0, v[52:53]
	v_mad_i64_i32 v[48:49], s[12:13], v48, s30, v[54:55]
	v_lshl_add_u64 v[64:65], v[62:63], 0, v[50:51]
	global_load_ushort v72, v[42:43], off offset:2048
	global_load_dword v61, v[6:7], off
	global_load_dword v58, v[44:45], off
	global_load_ushort v86, v[48:49], off
	global_load_ushort v74, v[64:65], off offset:2048
	global_load_ushort v75, v[46:47], off offset:2048
	v_add_u32_e32 v46, 18, v1
	v_add_u32_e32 v1, 19, v1
	v_mad_i64_i32 v[42:43], s[12:13], v46, s96, v[4:5]
	v_mad_i64_i32 v[4:5], s[12:13], v1, s96, v[4:5]
	v_lshl_add_u64 v[6:7], v[62:63], 0, v[52:53]
	v_lshl_add_u64 v[44:45], v[42:43], 0, v[50:51]
	v_lshl_add_u64 v[48:49], v[4:5], 0, v[50:51]
	v_lshl_add_u64 v[4:5], v[4:5], 0, v[52:53]
	v_lshl_add_u64 v[42:43], v[42:43], 0, v[52:53]
	v_mad_i64_i32 v[46:47], s[12:13], v46, s30, v[54:55]
	v_mad_i64_i32 v[64:65], s[12:13], v1, s30, v[54:55]
	global_load_dword v59, v[6:7], off
	global_load_dword v62, v[42:43], off
	global_load_ushort v98, v[46:47], off
	global_load_ushort v1, v[48:49], off offset:2048
	global_load_dword v63, v[4:5], off
	s_waitcnt lgkmcnt(0)
	global_load_ushort v101, v[64:65], off
	s_nop 0
	global_load_ushort v44, v[44:45], off offset:2048
	v_mad_i64_i32 v[4:5], s[12:13], v66, s30, v[54:55]
	v_mad_i64_i32 v[6:7], s[12:13], v70, s30, v[54:55]
	v_readlane_b32 s11, v254, 59
	global_load_ushort v108, v[6:7], off
	global_load_ushort v107, v[4:5], off
	v_mov_b32_e32 v4, s11
	ds_read_b64 v[4:5], v4
	v_mad_i64_i32 v[6:7], s[12:13], v71, s30, v[54:55]
	v_lshlrev_b32_e32 v45, 2, v3
	v_and_b32_e32 v46, 0x7c, v45
	s_waitcnt lgkmcnt(0)
	v_readfirstlane_b32 s11, v4
	v_readfirstlane_b32 s12, v5
	s_add_u32 s11, s11, s4
	s_addc_u32 s13, s12, s5
	s_lshl_b32 s12, s7, 9
	s_add_u32 s12, s11, s12
	s_addc_u32 s13, s13, 0
	v_lshlrev_b32_e32 v42, 2, v46
	v_mov_b32_e32 v43, v2
	v_lshl_add_u64 v[4:5], s[12:13], 0, v[42:43]
	global_load_ushort v89, v[6:7], off
	v_and_b32_e32 v87, 15, v3
	flat_load_dwordx4 v[4:7], v[4:5]
	s_add_u32 s12, s62, s6
	s_movk_i32 s6, 0x80
	s_addc_u32 s13, s63, 0
	v_cmp_gt_u32_e64 s[38:39], s6, v3
	s_lshl_b32 s6, s0, 4
	v_add_u32_e32 v88, 0, v45
	v_add_u32_e32 v45, 0, v42
	v_lshlrev_b32_e32 v42, 1, v46
	s_lshl_b32 s0, s0, 6
	v_lshlrev_b32_e32 v49, 2, v82
	v_lshl_add_u32 v91, v0, 2, 0
	v_cmp_gt_u32_e64 s[42:43], 32, v40
	v_mad_u32_u24 v46, v0, 44, v91
	v_mul_i32_i24_e32 v47, 0xffffffd4, v0
	s_waitcnt vmcnt(0)
	v_sub_f32_e32 v43, 1.0, v56
	v_max_f32_e32 v109, 0xda24260, v43
	v_mov_b32_e32 v166, v67
	v_sub_f32_e32 v43, 1.0, v57
	v_max_f32_e32 v110, 0xda24260, v43
	v_sub_f32_e32 v43, 1.0, v60
	v_max_f32_e32 v111, 0xda24260, v43
	v_and_b32_e32 v96, 48, v3
	v_cmp_lt_u32_e64 s[40:41], s51, v3
	v_or_b32_e32 v90, 2, v82
	v_mov_b32_e32 v167, v69
	v_mov_b32_e32 v169, v68
	v_lshl_add_u32 v92, v83, 3, v46
	v_add_u32_e32 v97, 0, v49
	v_cmp_gt_u32_e64 s[44:45], v82, v87
	v_cmp_lt_u32_e64 s[46:47], v82, v87
	v_cmp_gt_u32_e64 s[48:49], v90, v87
	s_mov_b32 s53, 0
	v_add_u32_e32 v104, v46, v47
	v_mov_b32_e32 v168, v72
	v_sub_f32_e32 v43, 1.0, v61
	v_max_f32_e32 v113, 0xda24260, v43
	v_sub_f32_e32 v43, 1.0, v58
	v_max_f32_e32 v112, 0xda24260, v43
	v_mov_b32_e32 v171, v75
	v_mov_b32_e32 v170, v74
	s_mov_b32 s54, 0
	v_sub_f32_e32 v43, 1.0, v59
	v_max_f32_e32 v114, 0xda24260, v43
	v_sub_f32_e32 v43, 1.0, v62
	v_mov_b32_e32 v172, v1
	v_sub_f32_e32 v1, 1.0, v63
	v_max_f32_e32 v116, 0xda24260, v1
	v_mul_u32_u24_e32 v1, 0x88, v87
	v_max_f32_e32 v115, 0xda24260, v43
	v_mov_b32_e32 v43, v2
	v_lshl_add_u32 v48, v1, 1, 0
	v_or_b32_e32 v1, s6, v87
	v_lshl_add_u64 v[64:65], s[12:13], 0, v[42:43]
	v_mad_u64_u32 v[66:67], s[12:13], v1, 48, v[2:3]
	v_lshl_add_u32 v1, v87, 8, v48
	v_mov_b32_e32 v173, v44
	v_ashrrev_i32_e32 v44, 5, v3
	v_add3_u32 v95, v1, s0, v49
	s_movk_i32 s0, 0x210
	v_mul_lo_u32 v40, v44, s0
	s_movk_i32 s0, 0x220
	v_mad_u64_u32 v[0:1], s[12:13], v83, s0, v[0:1]
	v_lshl_add_u32 v93, v41, 4, v48
	v_lshlrev_b32_e32 v41, 1, v82
	v_add_u32_e32 v3, 0, v96
	v_lshl_add_u32 v99, v0, 1, 0
	v_or_b32_e32 v67, 3, v82
	v_mul_u32_u24_e32 v0, 48, v87
	s_or_b32 s0, s10, s1
	v_add_u32_e32 v94, v66, v41
	v_add_u32_e32 v100, v48, v41
	v_cmp_gt_u32_e64 s[50:51], v67, v87
	v_lshl_add_u64 v[68:69], s[8:9], 0, v[42:43]
	v_add_u32_e32 v102, s0, v78
	v_add_u32_e32 v103, s0, v44
	v_add_u32_e32 v105, v3, v0
	v_add_u32_e32 v106, v45, v40
	s_branch .LBB0_351
.LBB0_350:
	s_or_b64 exec, exec, s[0:1]
	ds_read_b128 v[124:127], v97 offset:21440
	s_waitcnt lgkmcnt(0)
	s_barrier
	s_add_i32 s54, s54, 1
	s_waitcnt lgkmcnt(0)
	v_pk_mul_f32 v[10:11], v[10:11], v[126:127]
	v_pk_mul_f32 v[8:9], v[8:9], v[124:125]
	s_add_i32 s53, s53, 32
	s_cmpk_eq_i32 s53, 0x100
	v_mfma_f32_16x16x32_bf16 v[8:11], v[44:47], v[40:43], v[8:11]
	ds_read_b128 v[40:43], v106 offset:23552
	s_waitcnt lgkmcnt(0)
	v_pk_mul_f32 v[0:1], v[42:43], v[42:43]
	v_pk_mul_f32 v[44:45], v[40:41], v[40:41]
	s_nop 0
	v_pk_mov_b32 v[46:47], v[44:45], v[0:1] op_sel:[1,0]
	v_mov_b32_e32 v45, v1
	v_pk_add_f32 v[0:1], v[46:47], v[44:45]
	s_waitcnt vmcnt(12)
	v_lshlrev_b32_e32 v44, 16, v80
	v_add_f32_e32 v0, v0, v1
	ds_bpermute_b32 v1, v119, v0
	v_and_b32_e32 v45, 0xffff0000, v80
	s_waitcnt lgkmcnt(0)
	v_add_f32_e32 v0, v0, v1
	ds_bpermute_b32 v1, v120, v0
	s_waitcnt lgkmcnt(0)
	v_add_f32_e32 v0, v0, v1
	ds_bpermute_b32 v1, v121, v0
	s_waitcnt lgkmcnt(0)
	v_add_f32_e32 v0, v0, v1
	ds_bpermute_b32 v1, v122, v0
	s_waitcnt lgkmcnt(0)
	v_add_f32_e32 v0, v0, v1
	ds_bpermute_b32 v1, v123, v0
	s_waitcnt lgkmcnt(0)
	v_add_f32_e32 v0, v0, v1
	v_fmamk_f32 v0, v0, 0x3c000000, v178
	v_cmp_gt_f32_e32 vcc, s34, v0
	v_mul_f32_e32 v1, 0x4b800000, v0
	s_nop 0
	v_cndmask_b32_e32 v0, v0, v1, vcc
	v_rsq_f32_e32 v0, v0
	s_nop 0
	v_mul_f32_e32 v1, 0x45800000, v0
	v_cndmask_b32_e32 v0, v0, v1, vcc
	v_pk_mul_f32 v[40:41], v[40:41], v[0:1] op_sel_hi:[1,0]
	v_pk_mul_f32 v[0:1], v[42:43], v[0:1] op_sel_hi:[1,0]
	v_pk_mul_f32 v[40:41], v[4:5], v[40:41]
	v_pk_mul_f32 v[0:1], v[6:7], v[0:1]
	v_lshlrev_b32_e32 v42, 16, v81
	v_and_b32_e32 v43, 0xffff0000, v81
	v_pk_mul_f32 v[40:41], v[40:41], v[44:45]
	v_pk_mul_f32 v[0:1], v[0:1], v[42:43]
	v_cvt_pk_bf16_f32 v40, v40, v41
	v_cvt_pk_bf16_f32 v41, v0, v1
	v_lshlrev_b64 v[0:1], 11, v[78:79]
	v_lshl_add_u64 v[0:1], v[64:65], 0, v[0:1]
	global_store_dwordx2 v[0:1], v[40:41], off
	s_cbranch_scc1 .LBB0_415
.LBB0_351:
	v_add_u32_e32 v78, s53, v103
	v_mad_i64_i32 v[0:1], s[0:1], v78, s30, v[68:69]
	global_load_dwordx2 v[80:81], v[0:1], off offset:1024
	v_sub_f32_e32 v0, 1.0, v56
	v_max_f32_e32 v109, 0xda24260, v0
	v_sub_f32_e32 v0, 1.0, v57
	v_max_f32_e32 v110, 0xda24260, v0
	v_sub_f32_e32 v0, 1.0, v60
	v_max_f32_e32 v111, 0xda24260, v0
	v_sub_f32_e32 v0, 1.0, v61
	v_max_f32_e32 v113, 0xda24260, v0
	v_lshlrev_b32_e32 v70, 16, v166
	v_lshlrev_b32_e32 v71, 16, v167
	v_lshlrev_b32_e32 v72, 16, v168
	v_lshlrev_b32_e32 v73, 16, v169
	v_cmp_gt_f32_e32 vcc, s34, v109
	v_mov_b32_e32 v41, 0
	s_nop 0
	v_cndmask_b32_e64 v0, 0, 32, vcc
	v_ldexp_f32 v0, v109, v0
	v_log_f32_e32 v0, v0
	v_cndmask_b32_e32 v3, 0, v188, vcc
	v_mul_f32_e32 v1, 0x3f317217, v0
	v_fma_f32 v1, v0, s97, -v1
	v_fmac_f32_e32 v1, 0x3377d1cf, v0
	v_fmac_f32_e32 v1, 0x3f317217, v0
	v_cmp_lt_f32_e64 s[0:1], |v0|, s35
	s_nop 1
	v_cndmask_b32_e64 v0, v0, v1, s[0:1]
	v_cmp_gt_f32_e64 s[0:1], s34, v110
	v_sub_f32_e32 v0, v0, v3
	v_add_f32_e32 v47, 0, v0
	v_cndmask_b32_e64 v1, 0, 32, s[0:1]
	v_ldexp_f32 v1, v110, v1
	v_log_f32_e32 v1, v1
	v_cndmask_b32_e64 v3, 0, v188, s[0:1]
	v_mul_f32_e32 v0, 0x3f317217, v1
	v_fma_f32 v0, v1, s97, -v0
	v_fmac_f32_e32 v0, 0x3377d1cf, v1
	v_fmac_f32_e32 v0, 0x3f317217, v1
	v_cmp_lt_f32_e64 vcc, |v1|, s35
	s_nop 1
	v_cndmask_b32_e32 v0, v1, v0, vcc
	v_cmp_gt_f32_e32 vcc, s34, v111
	v_sub_f32_e32 v0, v0, v3
	v_add_f32_e32 v46, v0, v47
	v_cndmask_b32_e64 v1, 0, 32, vcc
	v_ldexp_f32 v1, v111, v1
	v_log_f32_e32 v1, v1
	v_cndmask_b32_e32 v3, 0, v188, vcc
	v_mul_f32_e32 v0, 0x3f317217, v1
	v_fma_f32 v0, v1, s97, -v0
	v_fmac_f32_e32 v0, 0x3377d1cf, v1
	v_fmac_f32_e32 v0, 0x3f317217, v1
	v_cmp_lt_f32_e64 s[0:1], |v1|, s35
	s_nop 1
	v_cndmask_b32_e64 v0, v1, v0, s[0:1]
	v_cmp_gt_f32_e64 s[0:1], s34, v113
	v_sub_f32_e32 v0, v0, v3
	v_add_f32_e32 v3, v0, v46
	v_cndmask_b32_e64 v1, 0, 32, s[0:1]
	v_ldexp_f32 v1, v113, v1
	v_log_f32_e32 v1, v1
	s_nop 0
	v_mul_f32_e32 v0, 0x3f317217, v1
	v_fma_f32 v0, v1, s97, -v0
	v_fmac_f32_e32 v0, 0x3377d1cf, v1
	v_fmac_f32_e32 v0, 0x3f317217, v1
	v_cmp_lt_f32_e64 vcc, |v1|, s35
	s_nop 1
	v_cndmask_b32_e32 v0, v1, v0, vcc
	v_cndmask_b32_e64 v1, 0, v188, s[0:1]
	v_sub_f32_e32 v0, v0, v1
	v_add_f32_e32 v1, v0, v3
	ds_write_b32 v88, v1 offset:21504
	s_waitcnt lgkmcnt(0)
	s_barrier
	ds_read2st64_b32 v[42:43], v91 offset0:84 offset1:86
	ds_read2st64_b32 v[44:45], v91 offset0:88 offset1:90
	s_and_saveexec_b64 s[0:1], s[40:41]
	s_cbranch_execz .LBB0_359
	v_cmp_lt_i32_e32 vcc, 1, v83
	s_mov_b64 s[8:9], 0
	s_and_saveexec_b64 s[10:11], vcc
	s_xor_b64 s[10:11], exec, s[10:11]
	s_cbranch_execz .LBB0_411
	v_cmp_eq_u32_e32 vcc, 2, v83
	s_mov_b64 s[8:9], -1
	s_and_saveexec_b64 s[12:13], vcc
	s_cbranch_execz .LBB0_355
	s_waitcnt lgkmcnt(0)
	v_add_f32_e32 v41, v42, v43
	s_xor_b64 s[8:9], exec, -1

.LBB0_361:
	s_or_b64 exec, exec, s[0:1]
	s_cmp_lt_u32 s54, 7
	s_cselect_b64 s[8:9], -1, 0
	s_cmp_gt_u32 s54, 6
	v_add_u32_e32 v117, s53, v102
	s_cbranch_scc1 .Lhg3_tail0
	v_add_u32_e32 v3, 32, v117
	v_mov_b64_e32 v[0:1], s[82:83]
	v_mad_i64_i32 v[40:41], s[0:1], v3, s96, v[0:1]
	v_lshl_add_u64 v[42:43], v[40:41], 0, v[50:51]
	v_lshl_add_u64 v[40:41], v[40:41], 0, v[52:53]
	global_load_dword v56, v[40:41], off
	v_mad_i64_i32 v[40:41], s[0:1], v3, s30, v[54:55]
	v_add_u32_e32 v3, 33, v117
	global_load_ushort v84, v[40:41], off
	v_mad_i64_i32 v[40:41], s[0:1], v3, s96, v[0:1]
	v_lshl_add_u64 v[44:45], v[40:41], 0, v[50:51]
	v_lshl_add_u64 v[40:41], v[40:41], 0, v[52:53]
	global_load_ushort v166, v[44:45], off offset:2048
	s_nop 0
	global_load_ushort v167, v[42:43], off offset:2048
	global_load_dword v57, v[40:41], off
	v_mad_i64_i32 v[40:41], s[0:1], v3, s30, v[54:55]
	v_add_u32_e32 v3, 34, v117
	global_load_ushort v85, v[40:41], off
	v_mad_i64_i32 v[40:41], s[0:1], v3, s96, v[0:1]
	v_add_u32_e32 v46, 35, v117
	v_lshl_add_u64 v[42:43], v[40:41], 0, v[50:51]
	v_lshl_add_u64 v[40:41], v[40:41], 0, v[52:53]
	v_mad_i64_i32 v[0:1], s[0:1], v46, s96, v[0:1]
	global_load_dword v60, v[40:41], off
	v_lshl_add_u64 v[40:41], v[0:1], 0, v[50:51]
	v_lshl_add_u64 v[0:1], v[0:1], 0, v[52:53]
	global_load_ushort v168, v[40:41], off offset:2048
	s_nop 0
	global_load_ushort v169, v[42:43], off offset:2048
	global_load_dword v61, v[0:1], off
	v_mad_i64_i32 v[0:1], s[0:1], v3, s30, v[54:55]
	global_load_ushort v107, v[0:1], off
	v_mad_i64_i32 v[0:1], s[0:1], v46, s30, v[54:55]
	global_load_ushort v108, v[0:1], off
	s_branch .LBB0_363

.LBB0_363:
	s_waitcnt lgkmcnt(0)
	s_barrier
	ds_read_b128 v[40:43], v93 offset:4352
	ds_read_b128 v[118:121], v93
	ds_read2_b64 v[122:125], v100 offset1:4
	ds_read_b128 v[126:129], v93 offset:4416
	ds_read_b128 v[130:133], v93 offset:64
	ds_read_b128 v[134:137], v93 offset:4480
	v_cvt_pk_bf16_f32 v44, v36, v37
	v_cvt_pk_bf16_f32 v45, v38, v39
	v_cvt_pk_bf16_f32 v46, v32, v33
	s_waitcnt lgkmcnt(4)
	v_mfma_f32_16x16x32_bf16 v[40:43], v[40:43], v[118:121], 0
	v_cvt_pk_bf16_f32 v47, v34, v35
	ds_read2_b64 v[138:141], v100 offset0:8 offset1:12
	ds_read_b128 v[142:145], v93 offset:128
	ds_read_b128 v[158:161], v93 offset:4544
	v_cvt_pk_bf16_f32 v118, v28, v29
	s_waitcnt lgkmcnt(4)
	v_mfma_f32_16x16x32_bf16 v[40:43], v[126:129], v[130:133], v[40:43]
	ds_read_b128 v[130:133], v93 offset:192
	v_cvt_pk_bf16_f32 v119, v30, v31
	v_cvt_pk_bf16_f32 v120, v24, v25
	v_cvt_pk_bf16_f32 v121, v26, v27
	s_waitcnt lgkmcnt(2)
	v_mfma_f32_16x16x32_bf16 v[40:43], v[134:137], v[142:145], v[40:43]
	v_cvt_pk_bf16_f32 v126, v20, v21
	v_cvt_pk_bf16_f32 v127, v22, v23
	v_cvt_pk_bf16_f32 v128, v16, v17
	v_mfma_f32_16x16x32_bf16 v[44:47], v[44:47], v[122:125], 0
	v_cvt_pk_bf16_f32 v129, v18, v19
	ds_read2_b64 v[134:137], v100 offset0:16 offset1:20
	ds_read2_b64 v[122:125], v100 offset0:24 offset1:28
	s_waitcnt lgkmcnt(2)
	v_mfma_f32_16x16x32_bf16 v[40:43], v[158:161], v[130:133], v[40:43]
	v_cvt_pk_bf16_f32 v130, v12, v13
	v_cvt_pk_bf16_f32 v131, v14, v15
	v_cvt_pk_bf16_f32 v132, v8, v9
	v_mfma_f32_16x16x32_bf16 v[44:47], v[118:121], v[138:141], v[44:47]
	v_cvt_pk_bf16_f32 v133, v10, v11
	s_nop 2
	v_cndmask_b32_e64 v0, v40, 0, s[44:45]
	v_cndmask_b32_e64 v1, 0, v41, s[46:47]
	ds_read_b64 v[40:41], v94 offset:14848
	s_waitcnt lgkmcnt(2)
	v_mfma_f32_16x16x32_bf16 v[44:47], v[126:129], v[134:137], v[44:47]
	v_cndmask_b32_e64 v3, v42, 0, s[48:49]
	v_cndmask_b32_e64 v48, v43, 0, s[50:51]
	v_mov_b32_e32 v42, v2
	v_mov_b32_e32 v43, v2
	s_waitcnt lgkmcnt(1)
	v_mfma_f32_16x16x32_bf16 v[44:47], v[130:133], v[122:125], v[44:47]
	v_cvt_pk_bf16_f32 v0, v0, v1
	v_cvt_pk_bf16_f32 v1, v3, v48
	v_mov_b32_e32 v3, v2
	v_add_u32_e32 v118, v66, v96
	s_waitcnt lgkmcnt(0)
	v_mfma_f32_16x16x32_bf16 v[40:43], v[40:43], v[0:3], v[44:47]
	s_nop 2
	v_mov_b32_e32 v44, 0
	s_nop 3
	ds_write_b128 v95, v[40:43] offset:23552
	v_mov_b32_e32 v40, 0
	v_mov_b32_e32 v41, 0
	v_mov_b32_e32 v42, 0
	v_mov_b32_e32 v43, 0
	s_and_saveexec_b64 s[0:1], s[42:43]
	ds_read_b128 v[40:43], v118 offset:14848
	s_or_b64 exec, exec, s[0:1]
	v_mov_b32_e32 v45, 0
	v_mov_b32_e32 v46, 0
	v_mov_b32_e32 v47, 0
	s_and_saveexec_b64 s[0:1], s[42:43]
	ds_read_b128 v[44:47], v105 offset:8704
	s_or_b64 exec, exec, s[0:1]
	ds_read_b128 v[120:123], v97 offset:20992
	v_mov_b32_e32 v48, 0
	v_mov_b32_e32 v49, 0
	s_waitcnt lgkmcnt(0)
	v_pk_mul_f32 v[38:39], v[38:39], v[122:123]
	v_pk_mul_f32 v[36:37], v[36:37], v[120:121]
	s_nop 1
	v_mfma_f32_16x16x32_bf16 v[36:39], v[44:47], v[40:43], v[36:39]
	v_mov_b32_e32 v44, 0
	v_mov_b32_e32 v46, 0
	v_mov_b32_e32 v47, 0
	s_and_saveexec_b64 s[0:1], s[42:43]
	ds_read_b128 v[46:49], v105 offset:9472
	s_or_b64 exec, exec, s[0:1]
	ds_read_b128 v[120:123], v97 offset:21056
	v_mov_b32_e32 v45, 0
	s_waitcnt lgkmcnt(0)
	v_pk_mul_f32 v[34:35], v[34:35], v[122:123]
	v_pk_mul_f32 v[32:33], v[32:33], v[120:121]
	s_nop 1
	v_mfma_f32_16x16x32_bf16 v[32:35], v[46:49], v[40:43], v[32:35]
	v_mov_b32_e32 v46, 0
	v_mov_b32_e32 v47, 0
	s_and_saveexec_b64 s[0:1], s[42:43]
	ds_read_b128 v[44:47], v105 offset:10240
	s_or_b64 exec, exec, s[0:1]
	ds_read_b128 v[120:123], v97 offset:21120
	v_mov_b32_e32 v48, 0
	v_mov_b32_e32 v49, 0
	s_waitcnt lgkmcnt(0)
	v_pk_mul_f32 v[30:31], v[30:31], v[122:123]
	v_pk_mul_f32 v[28:29], v[28:29], v[120:121]
	s_nop 1
	v_mfma_f32_16x16x32_bf16 v[28:31], v[44:47], v[40:43], v[28:31]
	v_mov_b32_e32 v44, 0
	v_mov_b32_e32 v46, 0
	v_mov_b32_e32 v47, 0
	s_and_saveexec_b64 s[0:1], s[42:43]
	ds_read_b128 v[46:49], v105 offset:11008
	s_or_b64 exec, exec, s[0:1]
	ds_read_b128 v[120:123], v97 offset:21184
	v_mov_b32_e32 v45, 0
	s_waitcnt lgkmcnt(0)
	v_pk_mul_f32 v[26:27], v[26:27], v[122:123]
	v_pk_mul_f32 v[24:25], v[24:25], v[120:121]
	s_nop 1
	v_mfma_f32_16x16x32_bf16 v[24:27], v[46:49], v[40:43], v[24:27]
	v_mov_b32_e32 v46, 0
	v_mov_b32_e32 v47, 0
	s_and_saveexec_b64 s[0:1], s[42:43]
	ds_read_b128 v[44:47], v105 offset:11776
	s_or_b64 exec, exec, s[0:1]
	ds_read_b128 v[120:123], v97 offset:21248
	v_mov_b32_e32 v48, 0
	v_mov_b32_e32 v49, 0
	s_waitcnt lgkmcnt(0)
	v_pk_mul_f32 v[22:23], v[22:23], v[122:123]
	v_pk_mul_f32 v[20:21], v[20:21], v[120:121]
	s_nop 1
	v_mfma_f32_16x16x32_bf16 v[20:23], v[44:47], v[40:43], v[20:23]
	v_mov_b32_e32 v44, 0
	v_mov_b32_e32 v46, 0
	v_mov_b32_e32 v47, 0
	s_and_saveexec_b64 s[0:1], s[42:43]
	ds_read_b128 v[46:49], v105 offset:12544
	s_or_b64 exec, exec, s[0:1]
	ds_read_b128 v[120:123], v97 offset:21312
	v_mov_b32_e32 v45, 0
	s_waitcnt lgkmcnt(0)
	v_pk_mul_f32 v[18:19], v[18:19], v[122:123]
	v_pk_mul_f32 v[16:17], v[16:17], v[120:121]
	s_nop 1
	v_mfma_f32_16x16x32_bf16 v[16:19], v[46:49], v[40:43], v[16:19]
	v_mov_b32_e32 v46, 0
	v_mov_b32_e32 v47, 0
	s_and_saveexec_b64 s[0:1], s[42:43]
	ds_read_b128 v[44:47], v105 offset:13312
	s_or_b64 exec, exec, s[0:1]
	ds_read_b128 v[120:123], v97 offset:21376
	v_mov_b32_e32 v1, 0
	s_waitcnt lgkmcnt(0)
	v_pk_mul_f32 v[14:15], v[14:15], v[122:123]
	v_pk_mul_f32 v[12:13], v[12:13], v[120:121]
	s_nop 1
	v_mfma_f32_16x16x32_bf16 v[12:15], v[44:47], v[40:43], v[12:15]
	v_mov_b32_e32 v44, 0
	v_mov_b32_e32 v45, 0
	v_mov_b32_e32 v46, 0
	v_mov_b32_e32 v47, 0
	s_and_saveexec_b64 s[0:1], s[42:43]
	ds_read_b128 v[44:47], v105 offset:14080
	s_or_b64 exec, exec, s[0:1]
	ds_read_b128 v[120:123], v97 offset:21440
	s_waitcnt lgkmcnt(0)
	s_barrier
	v_cmp_lt_i32_e32 vcc, v182, v181
	s_waitcnt lgkmcnt(0)
	v_pk_mul_f32 v[10:11], v[10:11], v[122:123]
	v_pk_mul_f32 v[8:9], v[8:9], v[120:121]
	v_cndmask_b32_e32 v3, v179, v182, vcc
	v_lshlrev_b32_e32 v119, 2, v3
	v_mfma_f32_16x16x32_bf16 v[8:11], v[44:47], v[40:43], v[8:11]
	ds_read_b128 v[40:43], v106 offset:23552
	v_cmp_lt_i32_e32 vcc, v183, v181
	s_waitcnt lgkmcnt(0)
	v_pk_mul_f32 v[44:45], v[42:43], v[42:43]
	v_pk_mul_f32 v[46:47], v[40:41], v[40:41]
	s_nop 0
	v_pk_mov_b32 v[48:49], v[46:47], v[44:45] op_sel:[1,0]
	v_mov_b32_e32 v47, v45
	v_pk_add_f32 v[44:45], v[48:49], v[46:47]
	s_nop 0
	v_add_f32_e32 v0, v44, v45
	ds_bpermute_b32 v3, v119, v0
	s_waitcnt vmcnt(12)
	v_lshlrev_b32_e32 v44, 16, v80
	v_and_b32_e32 v45, 0xffff0000, v80
	s_waitcnt lgkmcnt(0)
	v_add_f32_e32 v0, v0, v3
	v_cndmask_b32_e32 v3, v179, v183, vcc
	v_lshlrev_b32_e32 v120, 2, v3
	ds_bpermute_b32 v3, v120, v0
	v_cmp_lt_i32_e32 vcc, v184, v181
	s_waitcnt lgkmcnt(0)
	v_add_f32_e32 v0, v0, v3
	v_cndmask_b32_e32 v3, v179, v184, vcc
	v_lshlrev_b32_e32 v121, 2, v3
	ds_bpermute_b32 v3, v121, v0
	v_cmp_lt_i32_e32 vcc, v185, v181
	s_waitcnt lgkmcnt(0)
	v_add_f32_e32 v0, v0, v3
	v_cndmask_b32_e32 v3, v179, v185, vcc
	v_lshlrev_b32_e32 v122, 2, v3
	ds_bpermute_b32 v3, v122, v0
	v_cmp_lt_i32_e32 vcc, v186, v181
	s_waitcnt lgkmcnt(0)
	v_add_f32_e32 v0, v0, v3
	v_cndmask_b32_e32 v3, v179, v186, vcc
	v_lshlrev_b32_e32 v123, 2, v3
	ds_bpermute_b32 v3, v123, v0
	s_waitcnt lgkmcnt(0)
	v_add_f32_e32 v0, v0, v3
	v_fmamk_f32 v0, v0, 0x3c000000, v178
	v_cmp_gt_f32_e32 vcc, s34, v0
	v_mul_f32_e32 v3, 0x4b800000, v0
	s_nop 0
	v_cndmask_b32_e32 v0, v0, v3, vcc
	v_rsq_f32_e32 v0, v0
	s_nop 0
	v_mul_f32_e32 v3, 0x45800000, v0
	v_cndmask_b32_e32 v0, v0, v3, vcc
	v_pk_mul_f32 v[40:41], v[40:41], v[0:1] op_sel_hi:[1,0]
	v_pk_mul_f32 v[42:43], v[42:43], v[0:1] op_sel_hi:[1,0]
	v_pk_mul_f32 v[40:41], v[4:5], v[40:41]
	v_pk_mul_f32 v[42:43], v[6:7], v[42:43]
	v_pk_mul_f32 v[40:41], v[40:41], v[44:45]
	v_lshlrev_b32_e32 v44, 16, v81
	v_and_b32_e32 v45, 0xffff0000, v81
	v_pk_mul_f32 v[42:43], v[42:43], v[44:45]
	v_cvt_pk_bf16_f32 v40, v40, v41
	v_cvt_pk_bf16_f32 v41, v42, v43
	v_lshlrev_b64 v[42:43], 11, v[78:79]
	v_lshl_add_u64 v[42:43], v[64:65], 0, v[42:43]
	v_add_u32_e32 v78, 16, v78
	global_store_dwordx2 v[42:43], v[40:41], off
	v_mad_i64_i32 v[40:41], s[0:1], v78, s30, v[68:69]
	global_load_dwordx2 v[80:81], v[40:41], off offset:1024
	v_sub_f32_e32 v0, 1.0, v58
	v_max_f32_e32 v112, 0xda24260, v0
	v_sub_f32_e32 v0, 1.0, v59
	v_max_f32_e32 v114, 0xda24260, v0
	v_sub_f32_e32 v0, 1.0, v62
	v_max_f32_e32 v115, 0xda24260, v0
	v_sub_f32_e32 v0, 1.0, v63
	v_max_f32_e32 v116, 0xda24260, v0
	v_lshlrev_b32_e32 v74, 16, v170
	v_lshlrev_b32_e32 v75, 16, v171
	v_lshlrev_b32_e32 v76, 16, v172
	v_lshlrev_b32_e32 v77, 16, v173
	v_cmp_gt_f32_e32 vcc, s34, v112
	s_nop 1
	v_cndmask_b32_e64 v0, 0, 32, vcc
	v_ldexp_f32 v0, v112, v0
	v_log_f32_e32 v0, v0
	s_nop 0
	v_mul_f32_e32 v3, 0x3f317217, v0
	v_fma_f32 v3, v0, s97, -v3
	v_fmac_f32_e32 v3, 0x3377d1cf, v0
	v_fmac_f32_e32 v3, 0x3f317217, v0
	v_cmp_lt_f32_e64 s[0:1], |v0|, s35
	s_nop 1
	v_cndmask_b32_e64 v0, v0, v3, s[0:1]
	v_cndmask_b32_e32 v3, 0, v188, vcc
	v_sub_f32_e32 v0, v0, v3
	v_cmp_gt_f32_e32 vcc, s34, v114
	v_add_f32_e32 v47, 0, v0
	s_nop 0
	v_cndmask_b32_e64 v0, 0, 32, vcc
	v_ldexp_f32 v0, v114, v0
	v_log_f32_e32 v0, v0
	s_nop 0
	v_mul_f32_e32 v3, 0x3f317217, v0
	v_fma_f32 v3, v0, s97, -v3
	v_fmac_f32_e32 v3, 0x3377d1cf, v0
	v_fmac_f32_e32 v3, 0x3f317217, v0
	v_cmp_lt_f32_e64 s[0:1], |v0|, s35
	s_nop 1
	v_cndmask_b32_e64 v0, v0, v3, s[0:1]
	v_cndmask_b32_e32 v3, 0, v188, vcc
	v_sub_f32_e32 v0, v0, v3
	v_cmp_gt_f32_e32 vcc, s34, v115
	v_add_f32_e32 v3, v0, v47
	s_nop 0
	v_cndmask_b32_e64 v0, 0, 32, vcc
	v_ldexp_f32 v0, v115, v0
	v_log_f32_e32 v0, v0
	s_nop 0
	v_mul_f32_e32 v40, 0x3f317217, v0
	v_fma_f32 v40, v0, s97, -v40
	v_fmac_f32_e32 v40, 0x3377d1cf, v0
	v_fmac_f32_e32 v40, 0x3f317217, v0
	v_cmp_lt_f32_e64 s[0:1], |v0|, s35
	s_nop 1
	v_cndmask_b32_e64 v0, v0, v40, s[0:1]
	v_cndmask_b32_e32 v40, 0, v188, vcc
	v_sub_f32_e32 v0, v0, v40
	v_cmp_gt_f32_e32 vcc, s34, v116
	v_add_f32_e32 v46, v0, v3
	s_nop 0
	v_cndmask_b32_e64 v0, 0, 32, vcc
	v_ldexp_f32 v0, v116, v0
	v_log_f32_e32 v0, v0
	s_nop 0
	v_mul_f32_e32 v40, 0x3f317217, v0
	v_fma_f32 v40, v0, s97, -v40
	v_fmac_f32_e32 v40, 0x3377d1cf, v0
	v_fmac_f32_e32 v40, 0x3f317217, v0
	v_cmp_lt_f32_e64 s[0:1], |v0|, s35
	s_nop 1
	v_cndmask_b32_e64 v0, v0, v40, s[0:1]
	v_cndmask_b32_e32 v40, 0, v188, vcc
	v_sub_f32_e32 v0, v0, v40
	v_add_f32_e32 v41, v0, v46
	ds_write_b32 v88, v41 offset:21504
	s_waitcnt lgkmcnt(0)
	s_barrier
	ds_read2st64_b32 v[42:43], v91 offset0:84 offset1:86
	ds_read2st64_b32 v[44:45], v91 offset0:88 offset1:90
	s_and_saveexec_b64 s[0:1], s[40:41]
	s_cbranch_execz .LBB0_389
	v_cmp_lt_i32_e32 vcc, 1, v83
	s_mov_b64 s[10:11], 0
	s_and_saveexec_b64 s[12:13], vcc
	s_xor_b64 s[12:13], exec, s[12:13]
	s_cbranch_execz .LBB0_413
	v_cmp_eq_u32_e32 vcc, 2, v83
	s_mov_b64 s[10:11], -1
	s_and_saveexec_b64 s[14:15], vcc
	s_cbranch_execz .LBB0_385
	s_waitcnt lgkmcnt(1)
	v_add_f32_e32 v1, v42, v43
	s_xor_b64 s[10:11], exec, -1

.LBB0_391:
	s_or_b64 exec, exec, s[0:1]
	s_andn2_b64 vcc, exec, s[8:9]
	s_cbranch_vccnz .Lhg3_tail1
	v_add_u32_e32 v3, 48, v117
	v_mov_b64_e32 v[0:1], s[82:83]
	v_mad_i64_i32 v[40:41], s[0:1], v3, s96, v[0:1]
	v_lshl_add_u64 v[42:43], v[40:41], 0, v[50:51]
	v_lshl_add_u64 v[40:41], v[40:41], 0, v[52:53]
	global_load_dword v58, v[40:41], off
	v_mad_i64_i32 v[40:41], s[0:1], v3, s30, v[54:55]
	v_add_u32_e32 v3, 49, v117
	global_load_ushort v86, v[40:41], off
	v_mad_i64_i32 v[40:41], s[0:1], v3, s96, v[0:1]
	v_lshl_add_u64 v[44:45], v[40:41], 0, v[50:51]
	v_lshl_add_u64 v[40:41], v[40:41], 0, v[52:53]
	global_load_ushort v170, v[44:45], off offset:2048
	s_nop 0
	global_load_ushort v171, v[42:43], off offset:2048
	global_load_dword v59, v[40:41], off
	v_mad_i64_i32 v[40:41], s[0:1], v3, s30, v[54:55]
	v_add_u32_e32 v3, 50, v117
	global_load_ushort v89, v[40:41], off
	v_mad_i64_i32 v[40:41], s[0:1], v3, s96, v[0:1]
	v_add_u32_e32 v46, 51, v117
	v_lshl_add_u64 v[42:43], v[40:41], 0, v[50:51]
	v_lshl_add_u64 v[40:41], v[40:41], 0, v[52:53]
	v_mad_i64_i32 v[0:1], s[0:1], v46, s96, v[0:1]
	global_load_dword v62, v[40:41], off
	v_lshl_add_u64 v[40:41], v[0:1], 0, v[50:51]
	v_lshl_add_u64 v[0:1], v[0:1], 0, v[52:53]
	global_load_ushort v172, v[40:41], off offset:2048
	s_nop 0
	global_load_ushort v173, v[42:43], off offset:2048
	global_load_dword v63, v[0:1], off
	v_mad_i64_i32 v[0:1], s[0:1], v3, s30, v[54:55]
	global_load_ushort v98, v[0:1], off
	v_mad_i64_i32 v[0:1], s[0:1], v46, s30, v[54:55]
	global_load_ushort v101, v[0:1], off
	s_branch .LBB0_393
.Lhg3_tail1:
	s_waitcnt vmcnt(0)
.LBB0_393:
	s_waitcnt lgkmcnt(0)
	s_barrier
	ds_read_b128 v[40:43], v93 offset:4352
	ds_read_b128 v[124:127], v93
	ds_read2_b64 v[128:131], v100 offset1:4
	ds_read_b128 v[132:135], v93 offset:4416
	ds_read_b128 v[136:139], v93 offset:64
	ds_read_b128 v[140:143], v93 offset:4480
	v_cvt_pk_bf16_f32 v44, v36, v37
	v_cvt_pk_bf16_f32 v45, v38, v39
	v_cvt_pk_bf16_f32 v46, v32, v33
	s_waitcnt lgkmcnt(4)
	v_mfma_f32_16x16x32_bf16 v[40:43], v[40:43], v[124:127], 0
	v_cvt_pk_bf16_f32 v47, v34, v35
	ds_read2_b64 v[144:147], v100 offset0:8 offset1:12
	ds_read_b128 v[158:161], v93 offset:128
	ds_read_b128 v[162:165], v93 offset:4544
	v_cvt_pk_bf16_f32 v124, v28, v29
	s_waitcnt lgkmcnt(4)
	v_mfma_f32_16x16x32_bf16 v[40:43], v[132:135], v[136:139], v[40:43]
	ds_read_b128 v[136:139], v93 offset:192
	v_cvt_pk_bf16_f32 v125, v30, v31
	v_cvt_pk_bf16_f32 v126, v24, v25
	v_cvt_pk_bf16_f32 v127, v26, v27
	s_waitcnt lgkmcnt(2)
	v_mfma_f32_16x16x32_bf16 v[40:43], v[140:143], v[158:161], v[40:43]
	v_cvt_pk_bf16_f32 v132, v20, v21
	v_cvt_pk_bf16_f32 v133, v22, v23
	v_cvt_pk_bf16_f32 v134, v16, v17
	v_mfma_f32_16x16x32_bf16 v[44:47], v[44:47], v[128:131], 0
	v_cvt_pk_bf16_f32 v135, v18, v19
	ds_read2_b64 v[140:143], v100 offset0:16 offset1:20
	ds_read2_b64 v[128:131], v100 offset0:24 offset1:28
	s_waitcnt lgkmcnt(2)
	v_mfma_f32_16x16x32_bf16 v[40:43], v[162:165], v[136:139], v[40:43]
	v_cvt_pk_bf16_f32 v136, v12, v13
	v_cvt_pk_bf16_f32 v137, v14, v15
	v_cvt_pk_bf16_f32 v138, v8, v9
	v_mfma_f32_16x16x32_bf16 v[44:47], v[124:127], v[144:147], v[44:47]
	v_cvt_pk_bf16_f32 v139, v10, v11
	s_nop 2
	v_cndmask_b32_e64 v0, v40, 0, s[44:45]
	v_cndmask_b32_e64 v1, 0, v41, s[46:47]
	ds_read_b64 v[40:41], v94 offset:14848
	s_waitcnt lgkmcnt(2)
	v_mfma_f32_16x16x32_bf16 v[44:47], v[132:135], v[140:143], v[44:47]
	v_cndmask_b32_e64 v3, v42, 0, s[48:49]
	v_cndmask_b32_e64 v48, v43, 0, s[50:51]
	v_mov_b32_e32 v42, v2
	v_mov_b32_e32 v43, v2
	s_waitcnt lgkmcnt(1)
	v_mfma_f32_16x16x32_bf16 v[44:47], v[136:139], v[128:131], v[44:47]
	v_cvt_pk_bf16_f32 v0, v0, v1
	v_cvt_pk_bf16_f32 v1, v3, v48
	v_mov_b32_e32 v3, v2
	s_waitcnt lgkmcnt(0)
	s_nop 0
	v_mfma_f32_16x16x32_bf16 v[40:43], v[40:43], v[0:3], v[44:47]
	s_nop 2
	v_mov_b32_e32 v44, 0
	s_nop 3
	ds_write_b128 v95, v[40:43] offset:23552
	v_mov_b32_e32 v40, 0
	v_mov_b32_e32 v41, 0
	v_mov_b32_e32 v42, 0
	v_mov_b32_e32 v43, 0
	s_and_saveexec_b64 s[0:1], s[42:43]
	ds_read_b128 v[40:43], v118 offset:14848
	s_or_b64 exec, exec, s[0:1]
	v_mov_b32_e32 v45, 0
	v_mov_b32_e32 v46, 0
	v_mov_b32_e32 v47, 0
	s_and_saveexec_b64 s[0:1], s[42:43]
	ds_read_b128 v[44:47], v105 offset:8704
	s_or_b64 exec, exec, s[0:1]
	ds_read_b128 v[124:127], v97 offset:20992
	v_mov_b32_e32 v48, 0
	v_mov_b32_e32 v49, 0
	s_waitcnt lgkmcnt(0)
	v_pk_mul_f32 v[38:39], v[38:39], v[126:127]
	v_pk_mul_f32 v[36:37], v[36:37], v[124:125]
	s_nop 1
	v_mfma_f32_16x16x32_bf16 v[36:39], v[44:47], v[40:43], v[36:39]
	v_mov_b32_e32 v44, 0
	v_mov_b32_e32 v46, 0
	v_mov_b32_e32 v47, 0
	s_and_saveexec_b64 s[0:1], s[42:43]
	ds_read_b128 v[46:49], v105 offset:9472
	s_or_b64 exec, exec, s[0:1]
	ds_read_b128 v[124:127], v97 offset:21056
	v_mov_b32_e32 v45, 0
	s_waitcnt lgkmcnt(0)
	v_pk_mul_f32 v[34:35], v[34:35], v[126:127]
	v_pk_mul_f32 v[32:33], v[32:33], v[124:125]
	s_nop 1
	v_mfma_f32_16x16x32_bf16 v[32:35], v[46:49], v[40:43], v[32:35]
	v_mov_b32_e32 v46, 0
	v_mov_b32_e32 v47, 0
	s_and_saveexec_b64 s[0:1], s[42:43]
	ds_read_b128 v[44:47], v105 offset:10240
	s_or_b64 exec, exec, s[0:1]
	ds_read_b128 v[124:127], v97 offset:21120
	v_mov_b32_e32 v48, 0
	v_mov_b32_e32 v49, 0
	s_waitcnt lgkmcnt(0)
	v_pk_mul_f32 v[30:31], v[30:31], v[126:127]
	v_pk_mul_f32 v[28:29], v[28:29], v[124:125]
	s_nop 1
	v_mfma_f32_16x16x32_bf16 v[28:31], v[44:47], v[40:43], v[28:31]
	v_mov_b32_e32 v44, 0
	v_mov_b32_e32 v46, 0
	v_mov_b32_e32 v47, 0
	s_and_saveexec_b64 s[0:1], s[42:43]
	ds_read_b128 v[46:49], v105 offset:11008
	s_or_b64 exec, exec, s[0:1]
	ds_read_b128 v[124:127], v97 offset:21184
	v_mov_b32_e32 v45, 0
	s_waitcnt lgkmcnt(0)
	v_pk_mul_f32 v[26:27], v[26:27], v[126:127]
	v_pk_mul_f32 v[24:25], v[24:25], v[124:125]
	s_nop 1
	v_mfma_f32_16x16x32_bf16 v[24:27], v[46:49], v[40:43], v[24:27]
	v_mov_b32_e32 v46, 0
	v_mov_b32_e32 v47, 0
	s_and_saveexec_b64 s[0:1], s[42:43]
	ds_read_b128 v[44:47], v105 offset:11776
	s_or_b64 exec, exec, s[0:1]
	ds_read_b128 v[124:127], v97 offset:21248
	v_mov_b32_e32 v48, 0
	v_mov_b32_e32 v49, 0
	s_waitcnt lgkmcnt(0)
	v_pk_mul_f32 v[22:23], v[22:23], v[126:127]
	v_pk_mul_f32 v[20:21], v[20:21], v[124:125]
	s_nop 1
	v_mfma_f32_16x16x32_bf16 v[20:23], v[44:47], v[40:43], v[20:23]
	v_mov_b32_e32 v44, 0
	v_mov_b32_e32 v46, 0
	v_mov_b32_e32 v47, 0
	s_and_saveexec_b64 s[0:1], s[42:43]
	ds_read_b128 v[46:49], v105 offset:12544
	s_or_b64 exec, exec, s[0:1]
	ds_read_b128 v[124:127], v97 offset:21312
	v_mov_b32_e32 v45, 0
	s_waitcnt lgkmcnt(0)
	v_pk_mul_f32 v[18:19], v[18:19], v[126:127]
	v_pk_mul_f32 v[16:17], v[16:17], v[124:125]
	s_nop 1
	v_mfma_f32_16x16x32_bf16 v[16:19], v[46:49], v[40:43], v[16:19]
	v_mov_b32_e32 v46, 0
	v_mov_b32_e32 v47, 0
	s_and_saveexec_b64 s[0:1], s[42:43]
	ds_read_b128 v[44:47], v105 offset:13312
	s_or_b64 exec, exec, s[0:1]
	ds_read_b128 v[124:127], v97 offset:21376
	s_waitcnt lgkmcnt(0)
	v_pk_mul_f32 v[14:15], v[14:15], v[126:127]
	v_pk_mul_f32 v[12:13], v[12:13], v[124:125]
	s_nop 1
	v_mfma_f32_16x16x32_bf16 v[12:15], v[44:47], v[40:43], v[12:15]
	v_mov_b32_e32 v44, 0
	v_mov_b32_e32 v45, 0
	v_mov_b32_e32 v46, 0
	v_mov_b32_e32 v47, 0
	s_and_saveexec_b64 s[0:1], s[42:43]
	s_cbranch_execz .LBB0_350
	ds_read_b128 v[44:47], v105 offset:14080
	s_branch .LBB0_350
